# P0 pack copies: consecutive 1 KiB per wave instruction (thread t copies quads t+512m), 16 quads in flight
# speedup vs baseline: 1.6089x; 1.0033x over previous
.LBB0_69:
	s_lshr_b32 s56, s78, 2
	v_mov_b32_e32 v86, v186
	v_mul_u32_u24_e32 v84, 12, v186
	v_mov_b32_e32 v85, 0
	v_lshl_add_u64 v[80:81], v[84:85], 0, v[20:21]
	v_lshl_add_u64 v[82:83], v[84:85], 0, v[22:23]
	s_mov_b64 s[60:61], exec
	s_mov_b64 s[62:63], 0x2000
.Lpk_loop:
	v_cmp_gt_u32_e32 vcc, s56, v86
	s_and_b64 exec, exec, vcc
	s_cbranch_execz .Lpk_done
	v_add_u32_e32 v87, 0x0, v86
	v_cmp_gt_u32_e32 vcc, s56, v87
	s_and_saveexec_b64 s[58:59], vcc
	global_load_dwordx4 v[88:91], v[80:81], off
	s_mov_b64 exec, s[58:59]
	v_lshl_add_u64 v[80:81], v[80:81], 0, s[62:63]
	v_add_u32_e32 v87, 0x200, v86
	v_cmp_gt_u32_e32 vcc, s56, v87
	s_and_saveexec_b64 s[58:59], vcc
	global_load_dwordx4 v[92:95], v[80:81], off
	s_mov_b64 exec, s[58:59]
	v_lshl_add_u64 v[80:81], v[80:81], 0, s[62:63]
	v_add_u32_e32 v87, 0x400, v86
	v_cmp_gt_u32_e32 vcc, s56, v87
	s_and_saveexec_b64 s[58:59], vcc
	global_load_dwordx4 v[96:99], v[80:81], off
	s_mov_b64 exec, s[58:59]
	v_lshl_add_u64 v[80:81], v[80:81], 0, s[62:63]
	v_add_u32_e32 v87, 0x600, v86
	v_cmp_gt_u32_e32 vcc, s56, v87
	s_and_saveexec_b64 s[58:59], vcc
	global_load_dwordx4 v[100:103], v[80:81], off
	s_mov_b64 exec, s[58:59]
	v_lshl_add_u64 v[80:81], v[80:81], 0, s[62:63]
	v_add_u32_e32 v87, 0x800, v86
	v_cmp_gt_u32_e32 vcc, s56, v87
	s_and_saveexec_b64 s[58:59], vcc
	global_load_dwordx4 v[104:107], v[80:81], off
	s_mov_b64 exec, s[58:59]
	v_lshl_add_u64 v[80:81], v[80:81], 0, s[62:63]
	v_add_u32_e32 v87, 0xa00, v86
	v_cmp_gt_u32_e32 vcc, s56, v87
	s_and_saveexec_b64 s[58:59], vcc
	global_load_dwordx4 v[108:111], v[80:81], off
	s_mov_b64 exec, s[58:59]
	v_lshl_add_u64 v[80:81], v[80:81], 0, s[62:63]
	v_add_u32_e32 v87, 0xc00, v86
	v_cmp_gt_u32_e32 vcc, s56, v87
	s_and_saveexec_b64 s[58:59], vcc
	global_load_dwordx4 v[112:115], v[80:81], off
	s_mov_b64 exec, s[58:59]
	v_lshl_add_u64 v[80:81], v[80:81], 0, s[62:63]
	v_add_u32_e32 v87, 0xe00, v86
	v_cmp_gt_u32_e32 vcc, s56, v87
	s_and_saveexec_b64 s[58:59], vcc
	global_load_dwordx4 v[116:119], v[80:81], off
	s_mov_b64 exec, s[58:59]
	v_lshl_add_u64 v[80:81], v[80:81], 0, s[62:63]
	v_add_u32_e32 v87, 0x1000, v86
	v_cmp_gt_u32_e32 vcc, s56, v87
	s_and_saveexec_b64 s[58:59], vcc
	global_load_dwordx4 v[120:123], v[80:81], off
	s_mov_b64 exec, s[58:59]
	v_lshl_add_u64 v[80:81], v[80:81], 0, s[62:63]
	v_add_u32_e32 v87, 0x1200, v86
	v_cmp_gt_u32_e32 vcc, s56, v87
	s_and_saveexec_b64 s[58:59], vcc
	global_load_dwordx4 v[124:127], v[80:81], off
	s_mov_b64 exec, s[58:59]
	v_lshl_add_u64 v[80:81], v[80:81], 0, s[62:63]
	v_add_u32_e32 v87, 0x1400, v86
	v_cmp_gt_u32_e32 vcc, s56, v87
	s_and_saveexec_b64 s[58:59], vcc
	global_load_dwordx4 v[128:131], v[80:81], off
	s_mov_b64 exec, s[58:59]
	v_lshl_add_u64 v[80:81], v[80:81], 0, s[62:63]
	v_add_u32_e32 v87, 0x1600, v86
	v_cmp_gt_u32_e32 vcc, s56, v87
	s_and_saveexec_b64 s[58:59], vcc
	global_load_dwordx4 v[132:135], v[80:81], off
	s_mov_b64 exec, s[58:59]
	v_lshl_add_u64 v[80:81], v[80:81], 0, s[62:63]
	v_add_u32_e32 v87, 0x1800, v86
	v_cmp_gt_u32_e32 vcc, s56, v87
	s_and_saveexec_b64 s[58:59], vcc
	global_load_dwordx4 v[136:139], v[80:81], off
	s_mov_b64 exec, s[58:59]
	v_lshl_add_u64 v[80:81], v[80:81], 0, s[62:63]
	v_add_u32_e32 v87, 0x1a00, v86
	v_cmp_gt_u32_e32 vcc, s56, v87
	s_and_saveexec_b64 s[58:59], vcc
	global_load_dwordx4 v[140:143], v[80:81], off
	s_mov_b64 exec, s[58:59]
	v_lshl_add_u64 v[80:81], v[80:81], 0, s[62:63]
	v_add_u32_e32 v87, 0x1c00, v86
	v_cmp_gt_u32_e32 vcc, s56, v87
	s_and_saveexec_b64 s[58:59], vcc
	global_load_dwordx4 v[144:147], v[80:81], off
	s_mov_b64 exec, s[58:59]
	v_lshl_add_u64 v[80:81], v[80:81], 0, s[62:63]
	v_add_u32_e32 v87, 0x1e00, v86
	v_cmp_gt_u32_e32 vcc, s56, v87
	s_and_saveexec_b64 s[58:59], vcc
	global_load_dwordx4 v[148:151], v[80:81], off
	s_mov_b64 exec, s[58:59]
	v_lshl_add_u64 v[80:81], v[80:81], 0, s[62:63]
	s_waitcnt vmcnt(0)
	v_add_u32_e32 v87, 0x0, v86
	v_cmp_gt_u32_e32 vcc, s56, v87
	s_and_saveexec_b64 s[58:59], vcc
	global_store_dwordx4 v[82:83], v[88:91], off
	s_mov_b64 exec, s[58:59]
	v_lshl_add_u64 v[82:83], v[82:83], 0, s[62:63]
	v_add_u32_e32 v87, 0x200, v86
	v_cmp_gt_u32_e32 vcc, s56, v87
	s_and_saveexec_b64 s[58:59], vcc
	global_store_dwordx4 v[82:83], v[92:95], off
	s_mov_b64 exec, s[58:59]
	v_lshl_add_u64 v[82:83], v[82:83], 0, s[62:63]
	v_add_u32_e32 v87, 0x400, v86
	v_cmp_gt_u32_e32 vcc, s56, v87
	s_and_saveexec_b64 s[58:59], vcc
	global_store_dwordx4 v[82:83], v[96:99], off
	s_mov_b64 exec, s[58:59]
	v_lshl_add_u64 v[82:83], v[82:83], 0, s[62:63]
	v_add_u32_e32 v87, 0x600, v86
	v_cmp_gt_u32_e32 vcc, s56, v87
	s_and_saveexec_b64 s[58:59], vcc
	global_store_dwordx4 v[82:83], v[100:103], off
	s_mov_b64 exec, s[58:59]
	v_lshl_add_u64 v[82:83], v[82:83], 0, s[62:63]
	v_add_u32_e32 v87, 0x800, v86
	v_cmp_gt_u32_e32 vcc, s56, v87
	s_and_saveexec_b64 s[58:59], vcc
	global_store_dwordx4 v[82:83], v[104:107], off
	s_mov_b64 exec, s[58:59]
	v_lshl_add_u64 v[82:83], v[82:83], 0, s[62:63]
	v_add_u32_e32 v87, 0xa00, v86
	v_cmp_gt_u32_e32 vcc, s56, v87
	s_and_saveexec_b64 s[58:59], vcc
	global_store_dwordx4 v[82:83], v[108:111], off
	s_mov_b64 exec, s[58:59]
	v_lshl_add_u64 v[82:83], v[82:83], 0, s[62:63]
	v_add_u32_e32 v87, 0xc00, v86
	v_cmp_gt_u32_e32 vcc, s56, v87
	s_and_saveexec_b64 s[58:59], vcc
	global_store_dwordx4 v[82:83], v[112:115], off
	s_mov_b64 exec, s[58:59]
	v_lshl_add_u64 v[82:83], v[82:83], 0, s[62:63]
	v_add_u32_e32 v87, 0xe00, v86
	v_cmp_gt_u32_e32 vcc, s56, v87
	s_and_saveexec_b64 s[58:59], vcc
	global_store_dwordx4 v[82:83], v[116:119], off
	s_mov_b64 exec, s[58:59]
	v_lshl_add_u64 v[82:83], v[82:83], 0, s[62:63]
	v_add_u32_e32 v87, 0x1000, v86
	v_cmp_gt_u32_e32 vcc, s56, v87
	s_and_saveexec_b64 s[58:59], vcc
	global_store_dwordx4 v[82:83], v[120:123], off
	s_mov_b64 exec, s[58:59]
	v_lshl_add_u64 v[82:83], v[82:83], 0, s[62:63]
	v_add_u32_e32 v87, 0x1200, v86
	v_cmp_gt_u32_e32 vcc, s56, v87
	s_and_saveexec_b64 s[58:59], vcc
	global_store_dwordx4 v[82:83], v[124:127], off
	s_mov_b64 exec, s[58:59]
	v_lshl_add_u64 v[82:83], v[82:83], 0, s[62:63]
	v_add_u32_e32 v87, 0x1400, v86
	v_cmp_gt_u32_e32 vcc, s56, v87
	s_and_saveexec_b64 s[58:59], vcc
	global_store_dwordx4 v[82:83], v[128:131], off
	s_mov_b64 exec, s[58:59]
	v_lshl_add_u64 v[82:83], v[82:83], 0, s[62:63]
	v_add_u32_e32 v87, 0x1600, v86
	v_cmp_gt_u32_e32 vcc, s56, v87
	s_and_saveexec_b64 s[58:59], vcc
	global_store_dwordx4 v[82:83], v[132:135], off
	s_mov_b64 exec, s[58:59]
	v_lshl_add_u64 v[82:83], v[82:83], 0, s[62:63]
	v_add_u32_e32 v87, 0x1800, v86
	v_cmp_gt_u32_e32 vcc, s56, v87
	s_and_saveexec_b64 s[58:59], vcc
	global_store_dwordx4 v[82:83], v[136:139], off
	s_mov_b64 exec, s[58:59]
	v_lshl_add_u64 v[82:83], v[82:83], 0, s[62:63]
	v_add_u32_e32 v87, 0x1a00, v86
	v_cmp_gt_u32_e32 vcc, s56, v87
	s_and_saveexec_b64 s[58:59], vcc
	global_store_dwordx4 v[82:83], v[140:143], off
	s_mov_b64 exec, s[58:59]
	v_lshl_add_u64 v[82:83], v[82:83], 0, s[62:63]
	v_add_u32_e32 v87, 0x1c00, v86
	v_cmp_gt_u32_e32 vcc, s56, v87
	s_and_saveexec_b64 s[58:59], vcc
	global_store_dwordx4 v[82:83], v[144:147], off
	s_mov_b64 exec, s[58:59]
	v_lshl_add_u64 v[82:83], v[82:83], 0, s[62:63]
	v_add_u32_e32 v87, 0x1e00, v86
	v_cmp_gt_u32_e32 vcc, s56, v87
	s_and_saveexec_b64 s[58:59], vcc
	global_store_dwordx4 v[82:83], v[148:151], off
	s_mov_b64 exec, s[58:59]
	v_lshl_add_u64 v[82:83], v[82:83], 0, s[62:63]
	v_add_u32_e32 v86, 0x2000, v86
	s_branch .Lpk_loop
